# merge phase: removed the vmcnt(0) drain in the per-unit accumulator-zeroing block (K-loop LDS-DMA queue and epilogue stores stay in flight across the unit boundary, as in the in-projection)
# baseline (speedup 1.0000x reference)
; #define PG8_BAR __builtin_amdgcn_s_barrier()
; template <class Epi, class Sched>
; __device__ __forceinline__ void gemm_phase(LAS unsigned char* lds, const int lda, const int ldb, const Sched& S, const Epi& E) {
;     ...
;         if (!has_next) break;
; #pragma unroll
;         for (int a = 0; a < 2; ++a)
; #pragma unroll
;             for (int b = 0; b < 2; ++b)
; #pragma unroll
;                 for (int m = 0; m < 4; ++m)
; #pragma unroll
;                     for (int n = 0; n < 2; ++n) acc[a][b][m][n] = (f32x4){0.f, 0.f, 0.f, 0.f};
;         cur = nxt; cA = nA; cB = nB; ++ui;
;         if (wr == 1) PG8_BAR;
.LBB0_661:
	s_add_i32 s24, s59, -2
	s_add_u32 s25, s36, 0x100
	v_mov_b32_e32 v2, 0
	s_addc_u32 s60, s37, 0
	s_mov_b32 s44, 0
	v_mov_b32_e32 v3, v2
	v_mov_b32_e32 v4, v2
	v_mov_b32_e32 v5, v2
	v_mov_b32_e32 v6, v2
	v_mov_b32_e32 v7, v2
	v_mov_b32_e32 v8, v2
	v_mov_b32_e32 v9, v2
	v_mov_b32_e32 v18, v2
	v_mov_b32_e32 v19, v2
	v_mov_b32_e32 v20, v2
	v_mov_b32_e32 v21, v2
	v_mov_b32_e32 v22, v2
	v_mov_b32_e32 v23, v2
	v_mov_b32_e32 v24, v2
	v_mov_b32_e32 v25, v2
	v_mov_b32_e32 v34, v2
	v_mov_b32_e32 v35, v2
	v_mov_b32_e32 v36, v2
	v_mov_b32_e32 v37, v2
	v_mov_b32_e32 v38, v2
	v_mov_b32_e32 v39, v2
	v_mov_b32_e32 v40, v2
	v_mov_b32_e32 v41, v2
	v_mov_b32_e32 v50, v2
	v_mov_b32_e32 v51, v2
	v_mov_b32_e32 v52, v2
	v_mov_b32_e32 v53, v2
	v_mov_b32_e32 v54, v2
	v_mov_b32_e32 v55, v2
	v_mov_b32_e32 v56, v2
	v_mov_b32_e32 v57, v2
	v_mov_b32_e32 v10, v2
	v_mov_b32_e32 v11, v2
	v_mov_b32_e32 v12, v2
	v_mov_b32_e32 v13, v2
	v_mov_b32_e32 v14, v2
	v_mov_b32_e32 v15, v2
	v_mov_b32_e32 v16, v2
	v_mov_b32_e32 v17, v2
	v_mov_b32_e32 v26, v2
	v_mov_b32_e32 v27, v2
	v_mov_b32_e32 v28, v2
	v_mov_b32_e32 v29, v2
	v_mov_b32_e32 v30, v2
	v_mov_b32_e32 v31, v2
	v_mov_b32_e32 v32, v2
	v_mov_b32_e32 v33, v2
	v_mov_b32_e32 v42, v2
	v_mov_b32_e32 v43, v2
	v_mov_b32_e32 v44, v2
	v_mov_b32_e32 v45, v2
	v_mov_b32_e32 v46, v2
	v_mov_b32_e32 v47, v2
	v_mov_b32_e32 v48, v2
	v_mov_b32_e32 v49, v2
	v_mov_b32_e32 v58, v2
	v_mov_b32_e32 v59, v2
	v_mov_b32_e32 v60, v2
	v_mov_b32_e32 v61, v2
	v_mov_b32_e32 v62, v2
	v_mov_b32_e32 v63, v2
	v_mov_b32_e32 v64, v2
	v_mov_b32_e32 v65, v2
	v_mov_b32_e32 v66, v2
	v_mov_b32_e32 v67, v2
	v_mov_b32_e32 v68, v2
	v_mov_b32_e32 v69, v2
	v_mov_b32_e32 v70, v2
	v_mov_b32_e32 v71, v2
	v_mov_b32_e32 v72, v2
	v_mov_b32_e32 v73, v2
	v_mov_b32_e32 v82, v2
	v_mov_b32_e32 v83, v2
	v_mov_b32_e32 v84, v2
	v_mov_b32_e32 v85, v2
	v_mov_b32_e32 v86, v2
	v_mov_b32_e32 v87, v2
	v_mov_b32_e32 v88, v2
	v_mov_b32_e32 v89, v2
	v_mov_b32_e32 v98, v2
	v_mov_b32_e32 v99, v2
	v_mov_b32_e32 v100, v2
	v_mov_b32_e32 v101, v2
	v_mov_b32_e32 v102, v2
	v_mov_b32_e32 v103, v2
	v_mov_b32_e32 v104, v2
	v_mov_b32_e32 v105, v2
	v_mov_b32_e32 v114, v2
	v_mov_b32_e32 v115, v2
	v_mov_b32_e32 v116, v2
	v_mov_b32_e32 v117, v2
	v_mov_b32_e32 v118, v2
	v_mov_b32_e32 v119, v2
	v_mov_b32_e32 v120, v2
	v_mov_b32_e32 v121, v2
	v_mov_b32_e32 v74, v2
	v_mov_b32_e32 v75, v2
	v_mov_b32_e32 v76, v2
	v_mov_b32_e32 v77, v2
	v_mov_b32_e32 v78, v2
	v_mov_b32_e32 v79, v2
	v_mov_b32_e32 v80, v2
	v_mov_b32_e32 v81, v2
	v_mov_b32_e32 v90, v2
	v_mov_b32_e32 v91, v2
	v_mov_b32_e32 v92, v2
	v_mov_b32_e32 v93, v2
	v_mov_b32_e32 v94, v2
	v_mov_b32_e32 v95, v2
	v_mov_b32_e32 v96, v2
	v_mov_b32_e32 v97, v2
	v_mov_b32_e32 v106, v2
	v_mov_b32_e32 v107, v2
	v_mov_b32_e32 v108, v2
	v_mov_b32_e32 v109, v2
	v_mov_b32_e32 v110, v2
	v_mov_b32_e32 v111, v2
	v_mov_b32_e32 v112, v2
	v_mov_b32_e32 v113, v2
	v_mov_b32_e32 v122, v2
	v_mov_b32_e32 v123, v2
	v_mov_b32_e32 v124, v2
	v_mov_b32_e32 v125, v2
	v_mov_b32_e32 v126, v2
	v_mov_b32_e32 v127, v2
	v_mov_b32_e32 v128, v2
	v_mov_b32_e32 v129, v2
